# phase-0 weight-tile loop software-pipelined by rotation: next tile's decode+loads issued behind the transposition barrier, current tile's convert/store runs under them
# baseline (speedup 1.0000x reference)
; __device__ __forceinline__ unsigned cvt_pk_bf16(float lo, float hi) { unsigned r; asm volatile("v_cvt_pk_bf16_f32 %0, %1, %2" : "=v"(r) : "v"(lo), "v"(hi)); return r; }
; __device__ __forceinline__ int early_tile(int k) { if (k < 1472) return k; k -= 1472; if (k < 704) return 2880 + k; k -= 704; if (k < 256) return 4288 + k; k -= 256; if (k < 64) return 4800 + k; k -= 64; return 4928 + k; }
; __device__ __forceinline__ void transpose_tile(const float* src, int ldsrc, int k0, int n0, bf16_t* dst, int ldd, const float* gain, int rowmode, float* T) {
;     const int tid = threadIdx.x;
;     { const int kk = tid >> 4, n4 = (tid & 15) * 4; const float* gp = gain ? gain : src;
;         const f32x4 v0 = *(const f32x4*)(src + (size_t)(k0 + kk) * ldsrc + n0 + n4), v1 = *(const f32x4*)(src + (size_t)(k0 + kk + 32) * ldsrc + n0 + n4);
;         float g0 = gp[k0 + kk], g1 = gp[k0 + kk + 32]; if (!gain) { g0 = 1.0f; g1 = 1.0f; }
; #pragma unroll
;         for (int j = 0; j < 4; ++j) { T[(n4 + j) * 65 + kk] = v0[j] * g0; T[(n4 + j) * 65 + kk + 32] = v1[j] * g1; } }
;     __syncthreads();
;     { const int n = tid >> 3, k8 = (tid & 7) * 8; const float* tp = T + n * 65 + k8; u32x4 w;
;         w.x = cvt_pk_bf16(tp[0], tp[1]); w.y = cvt_pk_bf16(tp[2], tp[3]); w.z = cvt_pk_bf16(tp[4], tp[5]); w.w = cvt_pk_bf16(tp[6], tp[7]);
;         const int nn = n0 + n; int row;
;         if (rowmode == 1) row = (nn >> 7) * 256 + (nn & 127);
;         else if (rowmode == 2) row = (nn >> 7) * 256 + 128 + (nn & 127);
;         else if (rowmode == 3) row = nn < 1024 ? nn : (nn < 2048 ? nn + 1024 : nn - 1024);
;         else row = nn;
;         *(u32x4*)(dst + (size_t)row * ldd + k0 + k8) = w; }
;     __syncthreads();
; __device__ __forceinline__ void prep_weights(const Params& P, float* T) {
;     unsigned char* ws = P.ws;
;     if (gridDim.x == 256) {
;         if (blockIdx.x < 16) { for (int k = N_EARLY - 128 + blockIdx.x; k < N_EARLY; k += 16) weight_tile(P, early_tile(k), T); }
;         else { for (int k = blockIdx.x - 16; k < N_EARLY - 128; k += 240) weight_tile(P, early_tile(k), T); }
.LBB0_1184:
	s_or_b64 exec, exec, s[12:13]
	s_load_dwordx2 s[16:17], s[0:1], 0xc0
	s_cmpk_lg_i32 s58, 0x100
	s_cselect_b64 s[18:19], -1, 0
	s_mov_b64 s[8:9], -1
	s_and_b64 vcc, exec, s[18:19]
	s_cbranch_vccnz .LBB0_1276
	s_cmp_gt_u32 s2, 15
	s_cbranch_scc0 .LBB0_1231
	s_add_i32 s3, s2, -16
	s_cmpk_gt_i32 s3, 0xc3f
	s_cbranch_scc1 .LBB0_1230
	s_load_dwordx4 s[8:11], s[0:1], 0x30
	s_load_dwordx2 s[22:23], s[0:1], 0x40
	s_load_dwordx2 s[24:25], s[0:1], 0x50
	s_load_dwordx2 s[26:27], s[0:1], 0x68
	s_waitcnt lgkmcnt(0)
	s_add_u32 s28, s16, 0x2680000
	s_addc_u32 s29, s17, 0
	s_add_u32 s8, s8, 0x1000
	s_addc_u32 s9, s9, 0
	s_add_u32 s7, s16, 0x2580000
	s_addc_u32 s46, s17, 0
	s_add_u32 s47, s16, 0x2180000
	s_load_dwordx2 s[30:31], s[0:1], 0xb0
	s_load_dwordx4 s[12:15], s[0:1], 0xa0
	s_addc_u32 s48, s17, 0
	v_lshlrev_b32_e32 v0, 2, v210
	v_lshlrev_b32_e32 v2, 3, v210
	s_add_u32 s49, s16, 0x1680000
	v_lshrrev_b32_e32 v8, 4, v210
	v_and_b32_e32 v0, 60, v0
	v_lshrrev_b32_e32 v9, 3, v210
	v_and_b32_e32 v2, 56, v2
	s_addc_u32 s60, s17, 0
	v_mov_b32_e32 v5, 0
	v_lshl_add_u32 v1, v8, 2, 0
	v_mul_u32_u24_e32 v3, 0x104, v0
	v_mul_u32_u24_e32 v4, 0x104, v9
	v_lshlrev_b32_e32 v6, 2, v2
	s_add_u32 s61, s16, 0x80000
	s_mov_b32 s21, 0
	v_add3_u32 v10, 0, v4, v6
	s_addc_u32 s62, s17, 0
	s_add_i32 s63, s2, 0x970
	v_lshlrev_b32_e32 v4, 2, v0
	v_add_u32_e32 v11, v1, v3
	s_movk_i32 s64, 0x800
	s_movk_i32 s65, 0x3ff
	s_movk_i32 s70, 0x3f00
	s_movk_i32 s71, 0x80
	v_lshlrev_b32_e32 v6, 1, v2
	v_mov_b32_e32 v7, v5
	s_waitcnt vmcnt(1)
	v_mov_b32_e32 v12, 0xfffffc00
	v_mov_b32_e32 v13, 0x400
	s_mov_b32 s32, 0
	s_branch .LBB0_1190

; __device__ __forceinline__ unsigned cvt_pk_bf16(float lo, float hi) { unsigned r; asm volatile("v_cvt_pk_bf16_f32 %0, %1, %2" : "=v"(r) : "v"(lo), "v"(hi)); return r; }
; __device__ __forceinline__ void transpose_tile(const float* src, int ldsrc, int k0, int n0, bf16_t* dst, int ldd, const float* gain, int rowmode, float* T) {
;     ...
;         const f32x4 v0 = *(const f32x4*)(src + (size_t)(k0 + kk) * ldsrc + n0 + n4), v1 = *(const f32x4*)(src + (size_t)(k0 + kk + 32) * ldsrc + n0 + n4);
;         float g0 = gp[k0 + kk], g1 = gp[k0 + kk + 32]; if (!gain) { g0 = 1.0f; g1 = 1.0f; }
; #pragma unroll
;         for (int j = 0; j < 4; ++j) { T[(n4 + j) * 65 + kk] = v0[j] * g0; T[(n4 + j) * 65 + kk + 32] = v1[j] * g1; } }
;     __syncthreads();
;     { const int n = tid >> 3, k8 = (tid & 7) * 8; const float* tp = T + n * 65 + k8; u32x4 w;
;         w.x = cvt_pk_bf16(tp[0], tp[1]); w.y = cvt_pk_bf16(tp[2], tp[3]); w.z = cvt_pk_bf16(tp[4], tp[5]); w.w = cvt_pk_bf16(tp[6], tp[7]);
;         const int nn = n0 + n; int row;
;         if (rowmode == 1) row = (nn >> 7) * 256 + (nn & 127);
;         else if (rowmode == 2) row = (nn >> 7) * 256 + 128 + (nn & 127);
;         else if (rowmode == 3) row = nn < 1024 ? nn : (nn < 2048 ? nn + 1024 : nn - 1024);
;         else row = nn;
;         *(u32x4*)(dst + (size_t)row * ldd + k0 + k8) = w; }
; __device__ __forceinline__ void weight_tile(const Params& P, int t, float* T) {
;     ...
;         const int kt = j / nnt, ntile = j % nnt; (void)nkt;
;         transpose_tile(src, ldsrc, kt * 64, ntile * 64, dst, ldd, gain, rowmode, T);
.LBB0_1220:
	s_and_b32 s41, 0xffff, s20
	v_cvt_f32_u32_e32 v0, s41
	s_and_b32 s41, s75, 0xffff
	v_cvt_f32_u32_e32 v1, s41
	v_rcp_iflag_f32_e32 v2, v0
	s_nop 0
	v_mul_f32_e32 v2, v1, v2
	v_trunc_f32_e32 v2, v2
	v_cvt_u32_f32_e32 v3, v2
	v_fma_f32 v1, -v2, v0, v1
	v_cmp_ge_f32_e64 s[44:45], |v1|, v0
	s_cmp_lg_u64 s[44:45], 0
	v_readfirstlane_b32 s41, v3
	s_addc_u32 s41, s41, 0
	s_and_b32 s44, s41, 0xffff
	s_mul_i32 s41, s41, s20
	s_sub_i32 s20, s75, s41
	s_lshl_b32 s41, s44, 6
	s_lshl_b32 s44, s20, 6
	s_cmp_eq_u64 s[42:43], 0
	v_or_b32_e32 v14, s41, v8
	s_cselect_b64 s[76:77], -1, 0
	s_and_b64 s[78:79], s[76:77], exec
	v_add_u32_e32 v2, 32, v14
	s_cselect_b32 s43, s39, s43
	s_cselect_b32 s42, s38, s42
	v_mul_hi_u32_u24_e32 v1, s40, v14
	v_mul_u32_u24_e32 v0, s40, v14
	s_lshl_b32 s20, s20, 8
	v_mul_hi_u32_u24_e32 v3, s40, v2
	v_mul_u32_u24_e32 v2, s40, v2
	v_lshl_add_u64 v[0:1], v[0:1], 2, s[38:39]
	s_and_b32 s20, s20, 0x3ff00
	v_lshl_add_u64 v[2:3], v[2:3], 2, s[38:39]
	v_lshl_add_u64 v[0:1], v[0:1], 0, s[20:21]
	v_lshl_add_u64 v[2:3], v[2:3], 0, s[20:21]
	v_lshlrev_b32_e32 v14, 2, v14
	v_lshl_add_u64 v[0:1], v[0:1], 0, v[4:5]
	global_load_dword v18, v14, s[42:43]
	global_load_dword v19, v14, s[42:43] offset:128
	v_lshl_add_u64 v[14:15], v[2:3], 0, v[4:5]
	global_load_dwordx4 v[0:3], v[0:1], off
	s_nop 0
	global_load_dwordx4 v[14:17], v[14:15], off
	s_bitcmp1_b32 s32, 0
	s_cbranch_scc1 .Lrot0_tail
	s_and_b32 s20, 0xffff, s44
	s_cmp_lt_i32 s74, 2
	s_mov_b64 s[38:39], -1
	s_waitcnt vmcnt(3)
	v_cndmask_b32_e64 v18, v18, 1.0, s[76:77]
	s_waitcnt vmcnt(2)
	v_cndmask_b32_e64 v19, v19, 1.0, s[76:77]
	s_waitcnt vmcnt(1)
	v_mul_f32_e32 v0, v0, v18
	s_waitcnt vmcnt(0)
	v_mul_f32_e32 v14, v14, v19
	v_mul_f32_e32 v1, v1, v18
	v_mul_f32_e32 v15, v15, v19
	v_mul_f32_e32 v2, v2, v18
	v_mul_f32_e32 v16, v16, v19
	v_mul_f32_e32 v3, v3, v18
	v_mul_f32_e32 v17, v17, v19
	ds_write2_b32 v11, v0, v14 offset1:32
	ds_write2_b32 v11, v1, v15 offset0:65 offset1:97
	ds_write2_b32 v11, v2, v16 offset0:130 offset1:162
	ds_write2_b32 v11, v3, v17 offset0:195 offset1:227
	s_waitcnt lgkmcnt(0)
	s_barrier
	s_branch .Lrot0_save
.Lrot0_mid:
	s_and_b32 s20, 0xffff, s44
	s_cmp_lt_i32 s74, 2
	s_mov_b64 s[38:39], -1
	s_waitcnt vmcnt(4)
	v_cndmask_b32_e64 v18, v18, 1.0, s[76:77]
	s_waitcnt vmcnt(3)
	v_cndmask_b32_e64 v19, v19, 1.0, s[76:77]
	s_waitcnt vmcnt(2)
	v_mul_f32_e32 v0, v0, v18
	s_waitcnt vmcnt(1)
	v_mul_f32_e32 v14, v14, v19
	v_mul_f32_e32 v1, v1, v18
	v_mul_f32_e32 v15, v15, v19
	v_mul_f32_e32 v2, v2, v18
	v_mul_f32_e32 v16, v16, v19
	v_mul_f32_e32 v3, v3, v18
	v_mul_f32_e32 v17, v17, v19
	ds_write2_b32 v11, v0, v14 offset1:32
	ds_write2_b32 v11, v1, v15 offset0:65 offset1:97
	ds_write2_b32 v11, v2, v16 offset0:130 offset1:162
	ds_write2_b32 v11, v3, v17 offset0:195 offset1:227
	s_waitcnt lgkmcnt(0)
	s_barrier
.Lrot0_save:
	v_mov_b32_e32 v135, s20
	v_mov_b32_e32 v136, s36
	v_mov_b32_e32 v137, s37
	v_mov_b32_e32 v138, s34
	v_mov_b32_e32 v139, s35
	s_lshl_b32 s100, s41, 1
	v_mov_b32_e32 v140, s100
	v_mov_b32_e32 v141, 0
	s_mov_b32 s97, s74
	s_bitset1_b32 s32, 0
	s_cmpk_gt_i32 s72, 0xb4f
	s_cbranch_scc1 .Lrot0_last
	s_addk_i32 s3, 0xf0
	s_addk_i32 s63, 0xf0
	s_branch .LBB0_1190
.Lrot0_last:
	s_bitset1_b32 s32, 1
.Lrot0_tail:
	s_mov_b64 s[98:99], -1
	ds_read2_b32 v[142:143], v10 offset1:1
	s_waitcnt lgkmcnt(0)
	v_cvt_pk_bf16_f32 v142, v142, v143
	ds_read2_b32 v[144:145], v10 offset0:2 offset1:3
	s_waitcnt lgkmcnt(0)
	v_cvt_pk_bf16_f32 v143, v144, v145
	ds_read2_b32 v[144:145], v10 offset0:4 offset1:5
	s_waitcnt lgkmcnt(0)
	v_cvt_pk_bf16_f32 v144, v144, v145
	ds_read2_b32 v[146:147], v10 offset0:6 offset1:7
	s_waitcnt lgkmcnt(0)
	v_cvt_pk_bf16_f32 v145, v146, v147
	v_add_u32_e32 v146, v135, v9
	s_cmp_lt_i32 s97, 2
	s_cbranch_scc1 .LBB0_1226
	s_cmp_gt_i32 s97, 2
	s_cbranch_scc0 .LBB0_1223
	v_cmp_gt_u32_e32 vcc, s64, v146
	s_mov_b64 s[98:99], 0
	s_nop 0
	v_cndmask_b32_e32 v147, v12, v13, vcc
	v_cmp_lt_u32_e32 vcc, s65, v146
	s_nop 1
	v_cndmask_b32_e32 v147, 0, v147, vcc
	v_add_u32_e32 v147, v147, v146
.LBB0_1223:
	s_andn2_b64 vcc, exec, s[98:99]
	s_cbranch_vccnz .LBB0_1225
	v_lshlrev_b32_e32 v147, 1, v146
	v_and_b32_e32 v147, 0x3f00, v147
	v_and_b32_e32 v148, 0x7f, v146
	v_or3_b32 v147, v148, v147, s71
.LBB0_1225:
	s_mov_b64 s[98:99], 0
.LBB0_1226:
	s_andn2_b64 vcc, exec, s[98:99]
	s_cbranch_vccnz .LBB0_1189
	s_cmp_lg_u32 s97, 1
	s_cbranch_scc1 .LBB0_1188
	v_lshlrev_b32_e32 v147, 1, v146
	v_and_b32_e32 v146, 0x7f, v146
	v_and_or_b32 v146, v147, s70, v146
	s_branch .LBB0_1188
.LBB0_1188:
	v_mov_b32_e32 v147, v146
.LBB0_1189:
	v_mad_u64_u32 v[148:149], s[98:99], v136, v147, 0
	v_mov_b32_e32 v146, v149
	v_mad_u64_u32 v[146:147], s[98:99], v137, v147, v[146:147]
	v_mov_b32_e32 v149, v146
	v_lshl_add_u64 v[146:147], v[148:149], 1, v[138:139]
	v_lshl_add_u64 v[146:147], v[146:147], 0, v[140:141]
	v_lshl_add_u64 v[146:147], v[146:147], 0, v[6:7]
	global_store_dwordx4 v[146:147], v[142:145], off
	s_barrier
	s_bitcmp1_b32 s32, 1
	s_cbranch_scc1 .LBB0_1230
	s_branch .Lrot0_mid
